# proj GEMM: co-resident block pairs (bidx, bidx^256) re-synchronise once per tile through a bounded flag handshake in ws so their shared A-tile requests coincide
# speedup vs baseline: 1.0164x; 1.0093x over previous
; DEVI int tidx() { int t = threadIdx.x; asm volatile("" : "+v"(t)); return t; }
; DEVI void lds_barrier() { asm volatile("s_waitcnt lgkmcnt(0)\n\ts_barrier" ::: "memory"); }
; #define SSTORE2(P, buf_) do { \
;     *(uint4*)(wA + (buf_) * 256 * GS2) = P##a0; *(uint4*)(wA + (buf_) * 256 * GS2 + 64 * GS2) = P##a1; \
;     *(uint4*)(wA + (buf_) * 256 * GS2 + 128 * GS2) = P##a2; *(uint4*)(wA + (buf_) * 256 * GS2 + 192 * GS2) = P##a3; \
;     *(uint4*)(wB + (buf_) * 128 * GS2) = P##b0; *(uint4*)(wB + (buf_) * 128 * GS2 + 64 * GS2) = P##b1; } while (0)
; DEVI void gemm_kloop2(const bf16_t* __restrict__ A, size_t lda, const bf16_t* __restrict__ Bt, size_t ldb,
;                       const bf16_t* __restrict__ nA, size_t nlda, const bf16_t* __restrict__ nBt, size_t nldb,
;                       bool first, bf16_t* smem, f32x4 (&acc)[8][4]) {
;   const int tid = tidx(), lane = tid & 63, wave = tid >> 6, wr = wave >> 1, wc = wave & 1, r16 = lane & 15, g = lane >> 4;
;   bf16_t* sA0 = smem; bf16_t* sB0 = smem + 2 * 256 * GS2;
;   constexpr int nk = 32;
;   const int lrow = tid >> 2, lkc = (tid & 3) * 8;
;   const bf16_t* gA = A + (size_t)lrow * lda + lkc;
;   const bf16_t* gB = Bt + (size_t)lrow * ldb + lkc;
;   const bf16_t* hA = nA + (size_t)lrow * nlda + lkc;
;   const bf16_t* hB = nBt + (size_t)lrow * nldb + lkc;
;   bf16_t* wA = sA0 + lrow * GS2 + lkc;
;   bf16_t* wB = sB0 + lrow * GS2 + lkc;
;   uint4 xa0, xa1, xa2, xa3, xb0, xb1;
;   if (first) { GLOAD2(x, gA, gB, lda, ldb, 0); SSTORE2(x, 0); lds_barrier(); }
.LBB0_201:
	s_mul_hi_i32 s34, s41, 0x78787879
	s_lshr_b32 s35, s34, 31
	s_ashr_i32 s34, s34, 7
	s_add_i32 s34, s34, s35
	s_mul_i32 s35, s34, 0x110
	s_sub_i32 s35, s41, s35
	s_lshl_b32 s38, s34, 3
	s_add_i32 s38, s38, s40
	s_and_b32 s39, s35, 7
	s_or_b32 s34, s38, s39
	s_lshl_b32 s36, s34, 8
	s_lshl_b32 s35, s35, 4
	s_ashr_i32 s37, s36, 31
	s_and_b32 s34, s35, 0xffffff80
	s_lshl_b64 s[42:43], s[36:37], 11
	s_add_u32 s42, s20, s42
	s_addc_u32 s43, s21, s43
	s_ashr_i32 s35, s34, 31
	s_lshl_b64 s[44:45], s[34:35], 11
	s_add_u32 s44, s0, s44
	s_addc_u32 s45, s1, s45
	s_andn2_b64 vcc, exec, s[2:3]
	s_cbranch_vccnz .Lg1_warm
	v_and_b32_e32 v130, 63, v197
	v_lshrrev_b32_e32 v131, 6, v197
	v_lshrrev_b32_e32 v132, 3, v130
	v_readfirstlane_b32 s16, v131
	v_and_b32_e32 v133, 7, v130
	v_lshrrev_b32_e32 v134, 4, v130
	v_xor_b32_e32 v133, v133, v134
	v_xor_b32_e32 v134, 4, v133
	v_lshlrev_b32_e32 v133, 4, v133
	v_lshlrev_b32_e32 v134, 4, v134
	v_lshl_add_u32 v135, v131, 6, v132
	v_lshlrev_b32_e32 v135, 11, v135
	v_lshl_add_u32 v136, v131, 5, v132
	v_lshlrev_b32_e32 v136, 11, v136
	v_add_u32_e32 v200, v135, v133
	v_add_u32_e32 v201, v135, v134
	v_add_u32_e32 v201, 0x3c00, v201
	v_add_u32_e32 v202, v135, v133
	v_add_u32_e32 v202, 0x7800, v202
	v_add_u32_e32 v203, v135, v134
	v_add_u32_e32 v203, 0xb400, v203
	v_add_u32_e32 v204, v135, v133
	v_add_u32_e32 v204, 0x10000, v204
	v_add_u32_e32 v205, v135, v134
	v_add_u32_e32 v205, 0x13c00, v205
	v_add_u32_e32 v206, v135, v133
	v_add_u32_e32 v206, 0x17800, v206
	v_add_u32_e32 v207, v135, v134
	v_add_u32_e32 v207, 0x1b400, v207
	v_add_u32_e32 v208, v136, v133
	v_add_u32_e32 v209, v136, v134
	v_add_u32_e32 v209, 0x3c00, v209
	v_add_u32_e32 v210, v136, v133
	v_add_u32_e32 v210, 0x7800, v210
	v_add_u32_e32 v211, v136, v134
	v_add_u32_e32 v211, 0xb400, v211
	v_and_b32_e32 v132, 15, v130
	v_lshrrev_b32_e32 v133, 4, v130
	v_lshrrev_b32_e32 v134, 1, v132
	v_xor_b32_e32 v135, v133, v134
	v_xor_b32_e32 v136, 4, v135
	v_lshlrev_b32_e32 v135, 4, v135
	v_lshlrev_b32_e32 v136, 4, v136
	v_lshl_add_u32 v135, v132, 7, v135
	v_lshl_add_u32 v136, v132, 7, v136
	v_lshrrev_b32_e32 v134, 1, v131
	v_lshl_add_u32 v212, v134, 14, v135
	v_lshl_add_u32 v213, v134, 14, v136
	v_and_b32_e32 v134, 1, v131
	v_lshl_add_u32 v192, v134, 13, v135
	v_lshl_add_u32 v193, v134, 13, v136
	v_add_u32_e32 v192, 0x10000, v192
	v_add_u32_e32 v193, 0x10000, v193
	s_lshl_b32 s52, s16, 13
	s_lshl_b32 s53, s16, 12
	s_add_u32 s53, s53, 0x10000
	s_mov_b32 s50, 0
	s_mov_b32 s69, 0
	s_mov_b32 s82, 0
	v_readlane_b32 s84, v249, 39
	s_or_b32 s84, s84, 1
	s_lshl_b32 s84, s84, 8
	s_waitcnt vmcnt(0) lgkmcnt(0)
	s_barrier
	s_mov_b32 m0, s52
	s_nop 0
	global_load_lds_dwordx4 v200, s[42:43]
	global_load_lds_dwordx4 v201, s[42:43] offset:1024
	global_load_lds_dwordx4 v202, s[42:43] offset:2048
	global_load_lds_dwordx4 v203, s[42:43] offset:3072
	s_add_u32 m0, s52, 0x1000
	s_nop 0
	global_load_lds_dwordx4 v204, s[42:43]
	global_load_lds_dwordx4 v205, s[42:43] offset:1024
	global_load_lds_dwordx4 v206, s[42:43] offset:2048
	global_load_lds_dwordx4 v207, s[42:43] offset:3072
	s_mov_b32 m0, s53
	s_nop 0
	global_load_lds_dwordx4 v208, s[44:45]
	global_load_lds_dwordx4 v209, s[44:45] offset:1024
	global_load_lds_dwordx4 v210, s[44:45] offset:2048
	global_load_lds_dwordx4 v211, s[44:45] offset:3072
	s_branch .Lg1_go

; DEVI void phase_gemm_big(const Params& p, int mode, bf16_t* smem) {
;     ...
;   for (int L = li; L < per_xcd; L += nli) {
;     const int mg = L / (8 * NT), rem = L % (8 * NT), nt = rem >> 3, mt = xcd * 40 + mg * 8 + (rem & 7), m0 = mt * 256, n0 = nt * 128;
;     const int Ln = L + nli < per_xcd ? L + nli : L;
;     const int mgn = Ln / (8 * NT), remn = Ln % (8 * NT), m0n = (xcd * 40 + mgn * 8 + (remn & 7)) * 256, n0n = (remn >> 3) * 128;
.Lg1_go:
	s_add_u32 s86, s42, 0x80
	s_addc_u32 s87, s43, 0
	s_add_u32 s56, s44, 0x80
	s_addc_u32 s57, s45, 0
	s_add_i32 s35, s41, s83
	s_cmpk_gt_i32 s35, 0x54f
	s_cselect_b64 s[38:39], -1, 0
	s_cmpk_lt_i32 s35, 0x550
	s_cselect_b32 s2, s35, s41
	s_mul_hi_i32 s3, s2, 0x78787879
	s_lshr_b32 s37, s3, 31
	s_ashr_i32 s3, s3, 7
	s_add_i32 s3, s3, s37
	s_mul_i32 s37, s3, 0x110
	s_sub_i32 s2, s2, s37
	s_lshl_b32 s3, s3, 3
	s_add_i32 s3, s3, s40
	s_and_b32 s37, s2, 7
	s_or_b32 s3, s3, s37
	s_lshl_b32 s37, s2, 4
	s_lshl_b32 s2, s3, 8
	s_ashr_i32 s3, s2, 31
	s_and_b32 s42, s37, 0xffffff80
	s_lshl_b64 s[2:3], s[2:3], 11
	s_add_u32 s2, s20, s2
	s_addc_u32 s3, s21, s3
	s_ashr_i32 s43, s42, 31
	s_lshl_b64 s[42:43], s[42:43], 11
	s_add_u32 s42, s0, s42
	s_addc_u32 s43, s1, s43
	s_mov_b64 s[58:59], s[2:3]
	s_mov_b64 s[60:61], s[42:43]
	s_add_u32 s82, s82, 1
	s_cmp_lg_u32 s52, 0
	s_cbranch_scc1 .Lg1_hsd
	s_cmp_lg_u32 s83, 64
	s_cbranch_scc1 .Lg1_hsd
	v_readlane_b32 s16, v251, 0
	s_lshl_b32 s17, s16, 2
	s_add_u32 s42, s0, 0xf83600
	s_addc_u32 s43, s1, 0
	s_add_u32 s44, s42, s17
	s_addc_u32 s45, s43, 0
	s_xor_b32 s17, s17, 0x400
	s_add_u32 s42, s42, s17
	s_addc_u32 s43, s43, 0
	s_or_b32 s18, s84, s82
	s_mov_b64 s[2:3], exec
	s_mov_b64 exec, 1
	v_mov_b32_e32 v130, s18
	v_mov_b32_e32 v131, 0
	global_store_dword v131, v130, s[44:45] sc0 sc1
	s_movk_i32 s19, 0x1000
.Lg1_hsp:
	global_load_dword v132, v131, s[42:43] sc0 sc1
	s_waitcnt vmcnt(0)
	v_readfirstlane_b32 s37, v132
	s_cmp_ge_u32 s37, s18
	s_cbranch_scc1 .Lg1_hso
	s_sub_u32 s19, s19, 1
	s_cmp_eq_u32 s19, 0
	s_cbranch_scc1 .Lg1_hso
	s_sleep 1
	s_branch .Lg1_hsp
.Lg1_hso:
	s_mov_b64 exec, s[2:3]
	s_mov_b32 s69, 0
.Lg1_hsd:
	s_mov_b32 s65, 0
	s_bitcmp1_b32 s41, 5
	s_cbranch_scc0 .Lg1_np
	s_setprio 1

; DEVI unsigned xb_add(unsigned* p, unsigned v) { return __hip_atomic_fetch_add(p, v, __ATOMIC_RELAXED, __HIP_MEMORY_SCOPE_AGENT); }
; DEVI void grid_barrier(unsigned* bar, unsigned x, unsigned nloc, unsigned nx) {
;   asm volatile("s_waitcnt vmcnt(0)" ::: "memory");
;   __syncthreads();
;   if (threadIdx.x == 0) {
;     __builtin_amdgcn_s_waitcnt(0);
;     const unsigned old = xb_add(&bar[XB_XSUB(x)], 1u);
; DEVI void phase_gemm_big(const Params& p, int mode, bf16_t* smem) {
;     ...
;   __syncthreads();
.LBB0_209:
	v_readlane_b32 s16, v251, 0
	s_lshl_b32 s16, s16, 2
	s_add_u32 s42, s0, 0xf83600
	s_addc_u32 s43, s1, 0
	s_add_u32 s42, s42, s16
	s_addc_u32 s43, s43, 0
	v_readlane_b32 s17, v249, 39
	s_or_b32 s17, s17, 1
	s_lshl_b32 s17, s17, 8
	s_or_b32 s17, s17, 0xff
	s_mov_b64 s[2:3], exec
	s_mov_b64 exec, 1
	v_mov_b32_e32 v130, s17
	v_mov_b32_e32 v131, 0
	global_store_dword v131, v130, s[42:43] sc0 sc1
	s_mov_b64 exec, s[2:3]
	v_readlane_b32 s0, v249, 39
	s_or_b32 s26, s0, 2
	v_readlane_b32 s0, v250, 45
	v_readlane_b32 s1, v250, 46
	s_cmp_ge_i32 s26, s1
	s_waitcnt lgkmcnt(0)
	s_barrier
	s_cbranch_scc1 .LBB0_234
	s_waitcnt vmcnt(0)
	s_barrier
	s_mov_b64 s[0:1], exec
	v_readlane_b32 s2, v251, 5
	v_readlane_b32 s3, v251, 6
	s_and_b64 s[2:3], s[0:1], s[2:3]
	s_mov_b64 exec, s[2:3]
	s_cbranch_execz .LBB0_233
	s_mov_b64 s[2:3], exec
	v_mbcnt_lo_u32_b32 v0, s2, 0
	v_mbcnt_hi_u32_b32 v0, s3, v0
	v_cmp_eq_u32_e32 vcc, 0, v0
	s_waitcnt vmcnt(0) expcnt(0) lgkmcnt(0)
	s_and_saveexec_b64 s[20:21], vcc
	s_cbranch_execz .LBB0_213
	s_bcnt1_i32_b64 s2, s[2:3]
	v_mov_b32_e32 v2, s2
	v_readlane_b32 s2, v251, 7
	v_readlane_b32 s3, v251, 8
	s_nop 4
	global_atomic_add v2, v1, v2, s[2:3] sc0

; DEVI int tidx() { int t = threadIdx.x; asm volatile("" : "+v"(t)); return t; }
; DEVI void lds_barrier() { asm volatile("s_waitcnt lgkmcnt(0)\n\ts_barrier" ::: "memory"); }
; #define SSTORE2(P, buf_) do { \
;     *(uint4*)(wA + (buf_) * 256 * GS2) = P##a0; *(uint4*)(wA + (buf_) * 256 * GS2 + 64 * GS2) = P##a1; \
;     *(uint4*)(wA + (buf_) * 256 * GS2 + 128 * GS2) = P##a2; *(uint4*)(wA + (buf_) * 256 * GS2 + 192 * GS2) = P##a3; \
;     *(uint4*)(wB + (buf_) * 128 * GS2) = P##b0; *(uint4*)(wB + (buf_) * 128 * GS2 + 64 * GS2) = P##b1; } while (0)
; DEVI void gemm_kloop2(const bf16_t* __restrict__ A, size_t lda, const bf16_t* __restrict__ Bt, size_t ldb,
;                       const bf16_t* __restrict__ nA, size_t nlda, const bf16_t* __restrict__ nBt, size_t nldb,
;                       bool first, bf16_t* smem, f32x4 (&acc)[8][4]) {
;   const int tid = tidx(), lane = tid & 63, wave = tid >> 6, wr = wave >> 1, wc = wave & 1, r16 = lane & 15, g = lane >> 4;
;   bf16_t* sA0 = smem; bf16_t* sB0 = smem + 2 * 256 * GS2;
;   constexpr int nk = 32;
;   const int lrow = tid >> 2, lkc = (tid & 3) * 8;
;   const bf16_t* gA = A + (size_t)lrow * lda + lkc;
;   const bf16_t* gB = Bt + (size_t)lrow * ldb + lkc;
;   const bf16_t* hA = nA + (size_t)lrow * nlda + lkc;
;   const bf16_t* hB = nBt + (size_t)lrow * nldb + lkc;
;   bf16_t* wA = sA0 + lrow * GS2 + lkc;
;   bf16_t* wB = sB0 + lrow * GS2 + lkc;
;   uint4 xa0, xa1, xa2, xa3, xb0, xb1;
;   if (first) { GLOAD2(x, gA, gB, lda, ldb, 0); SSTORE2(x, 0); lds_barrier(); }
.LBB0_627:
	s_mul_hi_i32 s34, s41, 0x51eb851f
	s_lshr_b32 s35, s34, 31
	s_ashr_i32 s34, s34, 6
	s_add_i32 s34, s34, s35
	s_mul_i32 s35, s34, 0xc8
	s_sub_i32 s35, s41, s35
	s_lshl_b32 s38, s34, 3
	s_add_i32 s38, s38, s40
	s_and_b32 s39, s35, 7
	s_or_b32 s34, s38, s39
	s_lshl_b32 s36, s34, 8
	s_lshl_b32 s35, s35, 4
	s_ashr_i32 s37, s36, 31
	s_and_b32 s34, s35, 0xffffff80
	s_lshl_b64 s[42:43], s[36:37], 11
	s_add_u32 s42, s20, s42
	s_addc_u32 s43, s21, s43
	s_ashr_i32 s35, s34, 31
	s_lshl_b64 s[44:45], s[34:35], 11
	s_add_u32 s44, s0, s44
	s_addc_u32 s45, s1, s45
	s_andn2_b64 vcc, exec, s[2:3]
	s_cbranch_vccnz .Lg2_warm
	v_and_b32_e32 v130, 63, v197
	v_lshrrev_b32_e32 v131, 6, v197
	v_lshrrev_b32_e32 v132, 3, v130
	v_readfirstlane_b32 s16, v131
	v_and_b32_e32 v133, 7, v130
	v_lshrrev_b32_e32 v134, 4, v130
	v_xor_b32_e32 v133, v133, v134
	v_xor_b32_e32 v134, 4, v133
	v_lshlrev_b32_e32 v133, 4, v133
	v_lshlrev_b32_e32 v134, 4, v134
	v_lshl_add_u32 v135, v131, 6, v132
	v_lshlrev_b32_e32 v135, 11, v135
	v_lshl_add_u32 v136, v131, 5, v132
	v_lshlrev_b32_e32 v136, 11, v136
	v_add_u32_e32 v200, v135, v133
	v_add_u32_e32 v201, v135, v134
	v_add_u32_e32 v201, 0x3c00, v201
	v_add_u32_e32 v202, v135, v133
	v_add_u32_e32 v202, 0x7800, v202
	v_add_u32_e32 v203, v135, v134
	v_add_u32_e32 v203, 0xb400, v203
	v_add_u32_e32 v204, v135, v133
	v_add_u32_e32 v204, 0x10000, v204
	v_add_u32_e32 v205, v135, v134
	v_add_u32_e32 v205, 0x13c00, v205
	v_add_u32_e32 v206, v135, v133
	v_add_u32_e32 v206, 0x17800, v206
	v_add_u32_e32 v207, v135, v134
	v_add_u32_e32 v207, 0x1b400, v207
	v_add_u32_e32 v208, v136, v133
	v_add_u32_e32 v209, v136, v134
	v_add_u32_e32 v209, 0x3c00, v209
	v_add_u32_e32 v210, v136, v133
	v_add_u32_e32 v210, 0x7800, v210
	v_add_u32_e32 v211, v136, v134
	v_add_u32_e32 v211, 0xb400, v211
	v_and_b32_e32 v132, 15, v130
	v_lshrrev_b32_e32 v133, 4, v130
	v_lshrrev_b32_e32 v134, 1, v132
	v_xor_b32_e32 v135, v133, v134
	v_xor_b32_e32 v136, 4, v135
	v_lshlrev_b32_e32 v135, 4, v135
	v_lshlrev_b32_e32 v136, 4, v136
	v_lshl_add_u32 v135, v132, 7, v135
	v_lshl_add_u32 v136, v132, 7, v136
	v_lshrrev_b32_e32 v134, 1, v131
	v_lshl_add_u32 v212, v134, 14, v135
	v_lshl_add_u32 v213, v134, 14, v136
	v_and_b32_e32 v134, 1, v131
	v_lshl_add_u32 v192, v134, 13, v135
	v_lshl_add_u32 v193, v134, 13, v136
	v_add_u32_e32 v192, 0x10000, v192
	v_add_u32_e32 v193, 0x10000, v193
	s_lshl_b32 s52, s16, 13
	s_lshl_b32 s53, s16, 12
	s_add_u32 s53, s53, 0x10000
	s_mov_b32 s50, 0
	s_mov_b32 s69, 0
	s_mov_b32 s82, 0
	v_readlane_b32 s84, v249, 39
	s_or_b32 s84, s84, 6
	s_lshl_b32 s84, s84, 8
	s_waitcnt vmcnt(0) lgkmcnt(0)
	s_barrier
	s_mov_b32 m0, s52
	s_nop 0
	global_load_lds_dwordx4 v200, s[42:43]
	global_load_lds_dwordx4 v201, s[42:43] offset:1024
	global_load_lds_dwordx4 v202, s[42:43] offset:2048
	global_load_lds_dwordx4 v203, s[42:43] offset:3072
	s_add_u32 m0, s52, 0x1000
	s_nop 0
	global_load_lds_dwordx4 v204, s[42:43]
	global_load_lds_dwordx4 v205, s[42:43] offset:1024
	global_load_lds_dwordx4 v206, s[42:43] offset:2048
	global_load_lds_dwordx4 v207, s[42:43] offset:3072
	s_mov_b32 m0, s53
	s_nop 0
	global_load_lds_dwordx4 v208, s[44:45]
	global_load_lds_dwordx4 v209, s[44:45] offset:1024
	global_load_lds_dwordx4 v210, s[44:45] offset:2048
	global_load_lds_dwordx4 v211, s[44:45] offset:3072
	s_branch .Lg2_go

; DEVI void phase_gemm_big(const Params& p, int mode, bf16_t* smem) {
;     ...
;   for (int L = li; L < per_xcd; L += nli) {
;     const int mg = L / (8 * NT), rem = L % (8 * NT), nt = rem >> 3, mt = xcd * 40 + mg * 8 + (rem & 7), m0 = mt * 256, n0 = nt * 128;
;     const int Ln = L + nli < per_xcd ? L + nli : L;
;     const int mgn = Ln / (8 * NT), remn = Ln % (8 * NT), m0n = (xcd * 40 + mgn * 8 + (remn & 7)) * 256, n0n = (remn >> 3) * 128;
.Lg2_go:
	s_add_u32 s86, s42, 0x80
	s_addc_u32 s87, s43, 0
	s_add_u32 s56, s44, 0x80
	s_addc_u32 s57, s45, 0
	s_add_i32 s35, s41, s83
	s_cmpk_gt_i32 s35, 0x3e7
	s_cselect_b64 s[38:39], -1, 0
	s_cmpk_lt_i32 s35, 0x3e8
	s_cselect_b32 s2, s35, s41
	s_mul_hi_i32 s3, s2, 0x51eb851f
	s_lshr_b32 s37, s3, 31
	s_ashr_i32 s3, s3, 6
	s_add_i32 s3, s3, s37
	s_mul_i32 s37, s3, 0xc8
	s_sub_i32 s2, s2, s37
	s_lshl_b32 s3, s3, 3
	s_add_i32 s3, s3, s40
	s_and_b32 s37, s2, 7
	s_or_b32 s3, s3, s37
	s_lshl_b32 s37, s2, 4
	s_lshl_b32 s2, s3, 8
	s_ashr_i32 s3, s2, 31
	s_and_b32 s42, s37, 0xffffff80
	s_lshl_b64 s[2:3], s[2:3], 11
	s_add_u32 s2, s20, s2
	s_addc_u32 s3, s21, s3
	s_ashr_i32 s43, s42, 31
	s_lshl_b64 s[42:43], s[42:43], 11
	s_add_u32 s42, s0, s42
	s_addc_u32 s43, s1, s43
	s_mov_b64 s[58:59], s[2:3]
	s_mov_b64 s[60:61], s[42:43]
	s_add_u32 s82, s82, 1
	s_cmp_lg_u32 s52, 0
	s_cbranch_scc1 .Lg2_hsd
	s_cmp_lg_u32 s83, 64
	s_cbranch_scc1 .Lg2_hsd
	v_readlane_b32 s16, v251, 0
	s_lshl_b32 s17, s16, 2
	s_add_u32 s42, s0, 0xf83600
	s_addc_u32 s43, s1, 0
	s_add_u32 s44, s42, s17
	s_addc_u32 s45, s43, 0
	s_xor_b32 s17, s17, 0x400
	s_add_u32 s42, s42, s17
	s_addc_u32 s43, s43, 0
	s_or_b32 s18, s84, s82
	s_mov_b64 s[2:3], exec
	s_mov_b64 exec, 1
	v_mov_b32_e32 v130, s18
	v_mov_b32_e32 v131, 0
	global_store_dword v131, v130, s[44:45] sc0 sc1
	s_movk_i32 s19, 0x1000

; DEVI unsigned xb_add(unsigned* p, unsigned v) { return __hip_atomic_fetch_add(p, v, __ATOMIC_RELAXED, __HIP_MEMORY_SCOPE_AGENT); }
; DEVI void grid_barrier(unsigned* bar, unsigned x, unsigned nloc, unsigned nx) {
;   asm volatile("s_waitcnt vmcnt(0)" ::: "memory");
;   __syncthreads();
;   if (threadIdx.x == 0) {
;     __builtin_amdgcn_s_waitcnt(0);
;     const unsigned old = xb_add(&bar[XB_XSUB(x)], 1u);
; DEVI void phase_gemm_big(const Params& p, int mode, bf16_t* smem) {
;     ...
;   __syncthreads();
.LBB0_635:
	v_readlane_b32 s16, v251, 0
	s_lshl_b32 s16, s16, 2
	s_add_u32 s42, s0, 0xf83600
	s_addc_u32 s43, s1, 0
	s_add_u32 s42, s42, s16
	s_addc_u32 s43, s43, 0
	v_readlane_b32 s17, v249, 39
	s_or_b32 s17, s17, 6
	s_lshl_b32 s17, s17, 8
	s_or_b32 s17, s17, 0xff
	s_mov_b64 s[2:3], exec
	s_mov_b64 exec, 1
	v_mov_b32_e32 v130, s17
	v_mov_b32_e32 v131, 0
	global_store_dword v131, v130, s[42:43] sc0 sc1
	s_mov_b64 exec, s[2:3]
	v_readlane_b32 s0, v249, 39
	s_or_b32 s26, s0, 7
	v_readlane_b32 s0, v250, 45
	v_readlane_b32 s1, v250, 46
	s_cmp_ge_i32 s26, s1
	s_waitcnt lgkmcnt(0)
	s_barrier
	s_cbranch_scc1 .LBB0_660
	s_waitcnt vmcnt(0)
	s_barrier
	s_mov_b64 s[0:1], exec
	v_readlane_b32 s2, v251, 5
	v_readlane_b32 s3, v251, 6
	s_and_b64 s[2:3], s[0:1], s[2:3]
	s_mov_b64 exec, s[2:3]
	s_cbranch_execz .LBB0_659
	s_mov_b64 s[2:3], exec
	v_mbcnt_lo_u32_b32 v0, s2, 0
	v_mbcnt_hi_u32_b32 v0, s3, v0
	v_cmp_eq_u32_e32 vcc, 0, v0
	s_waitcnt vmcnt(0) expcnt(0) lgkmcnt(0)
	s_and_saveexec_b64 s[20:21], vcc
	s_cbranch_execz .LBB0_639
	s_bcnt1_i32_b64 s2, s[2:3]
	v_mov_b32_e32 v2, s2
	v_readlane_b32 s2, v251, 7
	v_readlane_b32 s3, v251, 8
	s_nop 4
	global_atomic_add v2, v1, v2, s[2:3] sc0

; DEVI int tidx() { int t = threadIdx.x; asm volatile("" : "+v"(t)); return t; }
; DEVI void lds_barrier() { asm volatile("s_waitcnt lgkmcnt(0)\n\ts_barrier" ::: "memory"); }
; #define SSTORE2(P, buf_) do { \
;     *(uint4*)(wA + (buf_) * 256 * GS2) = P##a0; *(uint4*)(wA + (buf_) * 256 * GS2 + 64 * GS2) = P##a1; \
;     *(uint4*)(wA + (buf_) * 256 * GS2 + 128 * GS2) = P##a2; *(uint4*)(wA + (buf_) * 256 * GS2 + 192 * GS2) = P##a3; \
;     *(uint4*)(wB + (buf_) * 128 * GS2) = P##b0; *(uint4*)(wB + (buf_) * 128 * GS2 + 64 * GS2) = P##b1; } while (0)
; DEVI void gemm_kloop2(const bf16_t* __restrict__ A, size_t lda, const bf16_t* __restrict__ Bt, size_t ldb,
;                       const bf16_t* __restrict__ nA, size_t nlda, const bf16_t* __restrict__ nBt, size_t nldb,
;                       bool first, bf16_t* smem, f32x4 (&acc)[8][4]) {
;   const int tid = tidx(), lane = tid & 63, wave = tid >> 6, wr = wave >> 1, wc = wave & 1, r16 = lane & 15, g = lane >> 4;
;   bf16_t* sA0 = smem; bf16_t* sB0 = smem + 2 * 256 * GS2;
;   constexpr int nk = 32;
;   const int lrow = tid >> 2, lkc = (tid & 3) * 8;
;   const bf16_t* gA = A + (size_t)lrow * lda + lkc;
;   const bf16_t* gB = Bt + (size_t)lrow * ldb + lkc;
;   const bf16_t* hA = nA + (size_t)lrow * nlda + lkc;
;   const bf16_t* hB = nBt + (size_t)lrow * nldb + lkc;
;   bf16_t* wA = sA0 + lrow * GS2 + lkc;
;   bf16_t* wB = sB0 + lrow * GS2 + lkc;
;   uint4 xa0, xa1, xa2, xa3, xb0, xb1;
;   if (first) { GLOAD2(x, gA, gB, lda, ldb, 0); SSTORE2(x, 0); lds_barrier(); }
.LBB0_1113:
	s_ashr_i32 s34, s41, 31
	s_lshr_b32 s34, s34, 24
	s_add_i32 s34, s41, s34
	s_ashr_i32 s35, s34, 8
	s_and_b32 s34, s34, 0xffffff00
	s_sub_i32 s34, s41, s34
	s_lshl_b32 s38, s35, 3
	s_add_i32 s38, s38, s40
	s_and_b32 s39, s34, 7
	s_or_b32 s35, s38, s39
	s_lshl_b32 s36, s35, 8
	s_lshl_b32 s34, s34, 4
	s_ashr_i32 s37, s36, 31
	s_and_b32 s34, s34, 0xffffff80
	s_lshl_b64 s[42:43], s[36:37], 11
	s_add_u32 s42, s20, s42
	s_addc_u32 s43, s21, s43
	s_ashr_i32 s35, s34, 31
	s_lshl_b64 s[44:45], s[34:35], 11
	s_add_u32 s44, s0, s44
	s_addc_u32 s45, s1, s45
	s_andn2_b64 vcc, exec, s[2:3]
	s_cbranch_vccnz .Lg3_warm
	v_and_b32_e32 v130, 63, v197
	v_lshrrev_b32_e32 v131, 6, v197
	v_lshrrev_b32_e32 v132, 3, v130
	v_readfirstlane_b32 s16, v131
	v_and_b32_e32 v133, 7, v130
	v_lshrrev_b32_e32 v134, 4, v130
	v_xor_b32_e32 v133, v133, v134
	v_xor_b32_e32 v134, 4, v133
	v_lshlrev_b32_e32 v133, 4, v133
	v_lshlrev_b32_e32 v134, 4, v134
	v_lshl_add_u32 v135, v131, 6, v132
	v_lshlrev_b32_e32 v135, 11, v135
	v_lshl_add_u32 v136, v131, 5, v132
	v_lshlrev_b32_e32 v136, 11, v136
	v_add_u32_e32 v200, v135, v133
	v_add_u32_e32 v201, v135, v134
	v_add_u32_e32 v201, 0x3c00, v201
	v_add_u32_e32 v202, v135, v133
	v_add_u32_e32 v202, 0x7800, v202
	v_add_u32_e32 v203, v135, v134
	v_add_u32_e32 v203, 0xb400, v203
	v_add_u32_e32 v204, v135, v133
	v_add_u32_e32 v204, 0x10000, v204
	v_add_u32_e32 v205, v135, v134
	v_add_u32_e32 v205, 0x13c00, v205
	v_add_u32_e32 v206, v135, v133
	v_add_u32_e32 v206, 0x17800, v206
	v_add_u32_e32 v207, v135, v134
	v_add_u32_e32 v207, 0x1b400, v207
	v_add_u32_e32 v208, v136, v133
	v_add_u32_e32 v209, v136, v134
	v_add_u32_e32 v209, 0x3c00, v209
	v_add_u32_e32 v210, v136, v133
	v_add_u32_e32 v210, 0x7800, v210
	v_add_u32_e32 v211, v136, v134
	v_add_u32_e32 v211, 0xb400, v211
	v_and_b32_e32 v132, 15, v130
	v_lshrrev_b32_e32 v133, 4, v130
	v_lshrrev_b32_e32 v134, 1, v132
	v_xor_b32_e32 v135, v133, v134
	v_xor_b32_e32 v136, 4, v135
	v_lshlrev_b32_e32 v135, 4, v135
	v_lshlrev_b32_e32 v136, 4, v136
	v_lshl_add_u32 v135, v132, 7, v135
	v_lshl_add_u32 v136, v132, 7, v136
	v_lshrrev_b32_e32 v134, 1, v131
	v_lshl_add_u32 v212, v134, 14, v135
	v_lshl_add_u32 v213, v134, 14, v136
	v_and_b32_e32 v134, 1, v131
	v_lshl_add_u32 v192, v134, 13, v135
	v_lshl_add_u32 v193, v134, 13, v136
	v_add_u32_e32 v192, 0x10000, v192
	v_add_u32_e32 v193, 0x10000, v193
	s_lshl_b32 s52, s16, 13
	s_lshl_b32 s53, s16, 12
	s_add_u32 s53, s53, 0x10000
	s_mov_b32 s50, 0
	s_mov_b32 s69, 0
	s_mov_b32 s82, 0
	v_readlane_b32 s84, v249, 39
	s_or_b32 s84, s84, 11
	s_lshl_b32 s84, s84, 8
	s_waitcnt vmcnt(0) lgkmcnt(0)
	s_barrier
	s_mov_b32 m0, s52
	s_nop 0
	global_load_lds_dwordx4 v200, s[42:43]
	global_load_lds_dwordx4 v201, s[42:43] offset:1024
	global_load_lds_dwordx4 v202, s[42:43] offset:2048
	global_load_lds_dwordx4 v203, s[42:43] offset:3072
	s_add_u32 m0, s52, 0x1000
	s_nop 0
	global_load_lds_dwordx4 v204, s[42:43]
	global_load_lds_dwordx4 v205, s[42:43] offset:1024
	global_load_lds_dwordx4 v206, s[42:43] offset:2048
	global_load_lds_dwordx4 v207, s[42:43] offset:3072
	s_mov_b32 m0, s53
	s_nop 0
	global_load_lds_dwordx4 v208, s[44:45]
	global_load_lds_dwordx4 v209, s[44:45] offset:1024
	global_load_lds_dwordx4 v210, s[44:45] offset:2048
	global_load_lds_dwordx4 v211, s[44:45] offset:3072
	s_branch .Lg3_go

; DEVI void phase_gemm_big(const Params& p, int mode, bf16_t* smem) {
;     ...
;   for (int L = li; L < per_xcd; L += nli) {
;     const int mg = L / (8 * NT), rem = L % (8 * NT), nt = rem >> 3, mt = xcd * 40 + mg * 8 + (rem & 7), m0 = mt * 256, n0 = nt * 128;
;     const int Ln = L + nli < per_xcd ? L + nli : L;
;     const int mgn = Ln / (8 * NT), remn = Ln % (8 * NT), m0n = (xcd * 40 + mgn * 8 + (remn & 7)) * 256, n0n = (remn >> 3) * 128;
.Lg3_go:
	s_add_u32 s86, s42, 0x80
	s_addc_u32 s87, s43, 0
	s_add_u32 s56, s44, 0x80
	s_addc_u32 s57, s45, 0
	s_add_i32 s35, s41, s83
	s_cmpk_gt_i32 s35, 0x4ff
	s_cselect_b64 s[38:39], -1, 0
	s_cmpk_lt_i32 s35, 0x500
	s_cselect_b32 s2, s35, s41
	s_ashr_i32 s3, s2, 31
	s_lshr_b32 s3, s3, 24
	s_add_i32 s3, s2, s3
	s_and_b32 s37, s3, 0xffffff00
	s_lshr_b32 s3, s3, 5
	s_sub_i32 s2, s2, s37
	s_and_b32 s3, s3, 0x7fffff8
	s_add_i32 s3, s3, s40
	s_and_b32 s37, s2, 7
	s_or_b32 s3, s3, s37
	s_lshl_b32 s37, s2, 4
	s_lshl_b32 s2, s3, 8
	s_ashr_i32 s3, s2, 31
	s_and_b32 s42, s37, 0xffffff80
	s_lshl_b64 s[2:3], s[2:3], 11
	s_add_u32 s2, s20, s2
	s_addc_u32 s3, s21, s3
	s_ashr_i32 s43, s42, 31
	s_lshl_b64 s[42:43], s[42:43], 11
	s_add_u32 s42, s0, s42
	s_addc_u32 s43, s1, s43
	s_mov_b64 s[58:59], s[2:3]
	s_mov_b64 s[60:61], s[42:43]
	s_add_u32 s82, s82, 1
	s_cmp_lg_u32 s52, 0
	s_cbranch_scc1 .Lg3_hsd
	s_cmp_lg_u32 s83, 64
	s_cbranch_scc1 .Lg3_hsd
	v_readlane_b32 s16, v251, 0
	s_lshl_b32 s17, s16, 2
	s_add_u32 s42, s0, 0xf83600
	s_addc_u32 s43, s1, 0
	s_add_u32 s44, s42, s17
	s_addc_u32 s45, s43, 0
	s_xor_b32 s17, s17, 0x400
	s_add_u32 s42, s42, s17
	s_addc_u32 s43, s43, 0
	s_or_b32 s18, s84, s82
	s_mov_b64 s[2:3], exec
	s_mov_b64 exec, 1
	v_mov_b32_e32 v130, s18
	v_mov_b32_e32 v131, 0
	global_store_dword v131, v130, s[44:45] sc0 sc1
	s_movk_i32 s19, 0x1000

; DEVI unsigned xb_add(unsigned* p, unsigned v) { return __hip_atomic_fetch_add(p, v, __ATOMIC_RELAXED, __HIP_MEMORY_SCOPE_AGENT); }
; DEVI void grid_barrier(unsigned* bar, unsigned x, unsigned nloc, unsigned nx) {
;   asm volatile("s_waitcnt vmcnt(0)" ::: "memory");
;   __syncthreads();
;   if (threadIdx.x == 0) {
;     __builtin_amdgcn_s_waitcnt(0);
;     const unsigned old = xb_add(&bar[XB_XSUB(x)], 1u);
; DEVI void phase_gemm_big(const Params& p, int mode, bf16_t* smem) {
;     ...
;   __syncthreads();
.LBB0_1121:
	v_readlane_b32 s16, v251, 0
	s_lshl_b32 s16, s16, 2
	s_add_u32 s42, s0, 0xf83600
	s_addc_u32 s43, s1, 0
	s_add_u32 s42, s42, s16
	s_addc_u32 s43, s43, 0
	v_readlane_b32 s17, v249, 39
	s_or_b32 s17, s17, 11
	s_lshl_b32 s17, s17, 8
	s_or_b32 s17, s17, 0xff
	s_mov_b64 s[2:3], exec
	s_mov_b64 exec, 1
	v_mov_b32_e32 v130, s17
	v_mov_b32_e32 v131, 0
	global_store_dword v131, v130, s[42:43] sc0 sc1
	s_mov_b64 exec, s[2:3]
	v_readlane_b32 s0, v249, 39
	s_or_b32 s26, s0, 12
	v_readlane_b32 s0, v250, 45
	v_readlane_b32 s1, v250, 46
	s_cmp_ge_i32 s26, s1
	s_waitcnt lgkmcnt(0)
	s_barrier
	s_cbranch_scc1 .LBB0_1146
	s_waitcnt vmcnt(0)
	s_barrier
	s_mov_b64 s[0:1], exec
	v_readlane_b32 s2, v251, 5
	v_readlane_b32 s3, v251, 6
	s_and_b64 s[2:3], s[0:1], s[2:3]
	s_mov_b64 exec, s[2:3]
	s_cbranch_execz .LBB0_1145
	s_mov_b64 s[2:3], exec
	v_mbcnt_lo_u32_b32 v0, s2, 0
	v_mbcnt_hi_u32_b32 v0, s3, v0
	v_cmp_eq_u32_e32 vcc, 0, v0
	s_waitcnt vmcnt(0) expcnt(0) lgkmcnt(0)
	s_and_saveexec_b64 s[20:21], vcc
	s_cbranch_execz .LBB0_1125
	s_bcnt1_i32_b64 s2, s[2:3]
	v_mov_b32_e32 v2, s2
	v_readlane_b32 s2, v251, 7
	v_readlane_b32 s3, v251, 8
	s_nop 4
	global_atomic_add v2, v1, v2, s[2:3] sc0
